# same GEMM K-loop trims applied to the K=256 and K=2048 instantiations
# baseline (speedup 1.0000x reference)
; #define PG8_STAGE(bufoff, gbase, voff) do { _Pragma("unroll") for (int _i = 0; _i < 2; ++_i) \
;         __builtin_amdgcn_global_load_lds((const unsigned*)((const char*)(gbase) + (voff)[_i]), (PG8_LAS unsigned*)(lds + (bufoff) + ldsw + _i * 8192), 16, 0, 0); } while (0)
; #define PG8_LDA(dst, b, h) do { _Pragma("unroll") for (int m = 0; m < 4; ++m) _Pragma("unroll") for (int k = 0; k < 2; ++k) dst[m][k] = *(const PG8_LAS bf16x8*)(lds + PG8_SA(b, h) + aoff + m * 2048 + k * 1024); } while (0)
; #define PG8_LDB(dst, b, h) do { _Pragma("unroll") for (int n = 0; n < 2; ++n) _Pragma("unroll") for (int k = 0; k < 2; ++k) dst[n][k] = *(const PG8_LAS bf16x8*)(lds + PG8_SB(b, h) + boff + n * 2048 + k * 1024); } while (0)
; #define PG8_MMA(ai, bj, At, Bt) do { __builtin_amdgcn_s_setprio(1); _Pragma("unroll") for (int m = 0; m < 4; ++m) _Pragma("unroll") for (int n = 0; n < 2; ++n) _Pragma("unroll") for (int k = 0; k < 2; ++k) \
;         acc[ai][bj][m][n] = __builtin_amdgcn_mfma_f32_16x16x32_bf16(Bt[n][k], At[m][k], acc[ai][bj][m][n], 0, 0, 0); __builtin_amdgcn_s_setprio(0); } while (0)
; #define PG8_WAIT_V(n) asm volatile("s_waitcnt vmcnt(" #n ")" ::: "memory")
; #define PG8_WAIT_L(n) asm volatile("s_waitcnt lgkmcnt(" #n ")" ::: "memory")
; #define PG8_BAR __builtin_amdgcn_s_barrier()
; #define PG8_SCHED __builtin_amdgcn_sched_barrier(0)
; template <class Epi, class Sched, bool ALIGN_EPI = false, bool SP2 = false>
; __device__ __forceinline__ void gemm_phase(PG8_LAS unsigned char* lds, const Gemm g, const Sched& S, const Epi& E, const int wave0) {
;     ...
;             const bool last = (t == nt - 2);
;             const char* a1 = cA + (size_t)(t + 1) * kstep;
;             const char* a2 = last ? nA : cA + (size_t)(t + 2) * kstep; const char* b2 = last ? nB : cB + (size_t)(t + 2) * kstep;
;             const char* a3 = a2 + kstep; const char* b3 = b2 + kstep;
;             if (last && has_next) S.a_ready(nxt);
;             if constexpr (SP2) {
;             PG8_LDB(B0, 0, 0); PG8_LDB(B1, 0, 1); PG8_SCHED; PG8_LDA(At, 0, 0); PG8_STAGE(PG8_SA(1, 1), a1 + hstep, voffA);
;             PG8_WAIT_V(8); PG8_WAIT_L(0); PG8_BAR; PG8_MMA(0, 0, At, B0); PG8_MMA(0, 1, At, B1); PG8_BAR; PG8_SCHED;
;             PG8_LDA(At, 0, 1); PG8_STAGE(PG8_SB(0, 0), b2, voffB); PG8_STAGE(PG8_SB(0, 1), b2 + hstep, voffB); PG8_STAGE(PG8_SA(0, 0), a2, voffA);
.LBB0_1258:
	s_add_u32 s59, s12, s58
	s_addc_u32 s64, s13, 0
	s_add_u32 s60, s59, 0x100
	s_addc_u32 s61, s64, 0
	s_and_b64 s[18:19], s[56:57], exec
	s_cselect_b32 s61, s9, s61
	s_cselect_b32 s60, s17, s60
	s_add_u32 s18, s10, s58
	s_addc_u32 s19, s11, 0
	s_add_u32 s58, s18, 0x100
	s_addc_u32 s62, s19, 0
	s_add_i32 vcc_hi, 0, 0x10000
	s_and_b64 s[18:19], s[56:57], exec
	s_cselect_b32 s63, s45, s62
	s_cselect_b32 s62, s47, s58
	s_add_i32 s18, 0, 0x14000
	s_add_u32 s66, s59, 0x10080
	s_addc_u32 s67, s64, 0
	s_add_i32 s87, vcc_hi, s95
	s_add_i32 m0, s33, 0xc000
	s_add_i32 s29, s33, 0xe000
	s_add_i32 s28, s87, 0x2000
	s_add_u32 s64, s62, 0x10000
	v_add_u32_e32 v140, vcc_hi, v238
	v_add_u32_e32 v156, s18, v238
	s_addc_u32 s65, s63, 0
	s_add_i32 vcc_lo, s18, s95
	ds_read_b128 v[64:67], v140
	ds_read_b128 v[132:135], v140 offset:1024
	ds_read_b128 v[136:139], v140 offset:2048
	ds_read_b128 v[140:143], v140 offset:3072
	ds_read_b128 v[144:147], v156
	ds_read_b128 v[148:151], v156 offset:1024
	ds_read_b128 v[152:155], v156 offset:2048
	ds_read_b128 v[156:159], v156 offset:3072
	s_add_i32 s88, vcc_lo, 0x2000
	s_add_i32 s86, 0, 0x18000
	s_add_i32 s80, 0, 0x1c000
	s_add_u32 s58, s60, 0x10000
	s_addc_u32 s59, s61, 0
	s_add_i32 s74, s86, s95
	s_add_i32 s72, s74, 0x2000
	s_add_u32 s56, s62, 0x10080
	s_addc_u32 s57, s63, 0
	s_add_i32 s19, s80, s95
	s_add_i32 s18, s19, 0x2000
	ds_read_b128 v[160:163], v239
	ds_read_b128 v[164:167], v239 offset:1024
	ds_read_b128 v[168:171], v239 offset:2048
	ds_read_b128 v[172:175], v239 offset:3072
	ds_read_b128 v[176:179], v239 offset:4096
	ds_read_b128 v[180:183], v239 offset:5120
	ds_read_b128 v[184:187], v239 offset:6144
	ds_read_b128 v[188:191], v239 offset:7168
	global_load_lds_dwordx4 v216, s[66:67]
	s_mov_b32 m0, s29
	s_nop 0
	global_load_lds_dwordx4 v218, s[66:67]
	s_waitcnt vmcnt(8)
	s_waitcnt lgkmcnt(0)
	s_barrier
	s_setprio 1
	v_mfma_f32_16x16x32_bf16 v[128:131], v[64:67], v[160:163], v[128:131]
	v_mfma_f32_16x16x32_bf16 v[124:127], v[136:139], v[160:163], v[124:127]
	v_mfma_f32_16x16x32_bf16 v[112:115], v[64:67], v[168:171], v[112:115]
	v_mfma_f32_16x16x32_bf16 v[104:107], v[136:139], v[168:171], v[104:107]
	v_mfma_f32_16x16x32_bf16 v[96:99], v[64:67], v[176:179], v[96:99]
	v_mfma_f32_16x16x32_bf16 v[88:91], v[136:139], v[176:179], v[88:91]
	v_mfma_f32_16x16x32_bf16 v[80:83], v[64:67], v[184:187], v[80:83]
	v_mfma_f32_16x16x32_bf16 v[72:75], v[136:139], v[184:187], v[72:75]
	v_mfma_f32_16x16x32_bf16 v[128:131], v[132:135], v[164:167], v[128:131]
	v_mfma_f32_16x16x32_bf16 v[124:127], v[140:143], v[164:167], v[124:127]
	v_mfma_f32_16x16x32_bf16 v[112:115], v[132:135], v[172:175], v[112:115]
	v_mfma_f32_16x16x32_bf16 v[104:107], v[140:143], v[172:175], v[104:107]
	v_mfma_f32_16x16x32_bf16 v[96:99], v[132:135], v[180:183], v[96:99]
	v_mfma_f32_16x16x32_bf16 v[88:91], v[140:143], v[180:183], v[88:91]
	v_mfma_f32_16x16x32_bf16 v[80:83], v[132:135], v[188:191], v[80:83]
	v_mfma_f32_16x16x32_bf16 v[72:75], v[140:143], v[188:191], v[72:75]
	v_mfma_f32_16x16x32_bf16 v[120:123], v[144:147], v[160:163], v[120:123]
	v_mfma_f32_16x16x32_bf16 v[116:119], v[152:155], v[160:163], v[116:119]
	v_mfma_f32_16x16x32_bf16 v[108:111], v[144:147], v[168:171], v[108:111]
	v_mfma_f32_16x16x32_bf16 v[100:103], v[152:155], v[168:171], v[100:103]
	v_mfma_f32_16x16x32_bf16 v[92:95], v[144:147], v[176:179], v[92:95]
	v_mfma_f32_16x16x32_bf16 v[84:87], v[152:155], v[176:179], v[84:87]
	v_mfma_f32_16x16x32_bf16 v[76:79], v[144:147], v[184:187], v[76:79]
	v_mfma_f32_16x16x32_bf16 v[68:71], v[152:155], v[184:187], v[68:71]
	v_mfma_f32_16x16x32_bf16 v[120:123], v[148:151], v[164:167], v[120:123]
	v_mfma_f32_16x16x32_bf16 v[116:119], v[156:159], v[164:167], v[116:119]
	v_mfma_f32_16x16x32_bf16 v[108:111], v[148:151], v[172:175], v[108:111]
	v_mfma_f32_16x16x32_bf16 v[100:103], v[156:159], v[172:175], v[100:103]
	v_mfma_f32_16x16x32_bf16 v[92:95], v[148:151], v[180:183], v[92:95]
	v_mfma_f32_16x16x32_bf16 v[84:87], v[156:159], v[180:183], v[84:87]
	v_mfma_f32_16x16x32_bf16 v[76:79], v[148:151], v[188:191], v[76:79]
	v_mfma_f32_16x16x32_bf16 v[68:71], v[156:159], v[188:191], v[68:71]
	s_setprio 0
	s_barrier
	s_mov_b32 m0, s87
	ds_read_b128 v[160:163], v239 offset:16384
	ds_read_b128 v[164:167], v239 offset:17408
	ds_read_b128 v[168:171], v239 offset:18432
	ds_read_b128 v[172:175], v239 offset:19456
	ds_read_b128 v[176:179], v239 offset:20480
	ds_read_b128 v[180:183], v239 offset:21504
	ds_read_b128 v[184:187], v239 offset:22528
	ds_read_b128 v[188:191], v239 offset:23552
	global_load_lds_dwordx4 v216, s[62:63]
	s_mov_b32 m0, s28
	s_nop 0
	global_load_lds_dwordx4 v218, s[62:63]
	s_mov_b32 m0, vcc_lo
	s_nop 0
	global_load_lds_dwordx4 v216, s[64:65]
	s_mov_b32 m0, s88
	s_nop 0
	global_load_lds_dwordx4 v218, s[64:65]
	s_mov_b32 m0, s33
	s_nop 0
	global_load_lds_dwordx4 v216, s[60:61]
	s_mov_b32 m0, s82
	s_nop 0
	global_load_lds_dwordx4 v218, s[60:61]
	s_waitcnt vmcnt(8)
	s_waitcnt lgkmcnt(0)
	s_barrier
; #define PG8_STAGE(bufoff, gbase, voff) do { _Pragma("unroll") for (int _i = 0; _i < 2; ++_i) \
;         __builtin_amdgcn_global_load_lds((const unsigned*)((const char*)(gbase) + (voff)[_i]), (PG8_LAS unsigned*)(lds + (bufoff) + ldsw + _i * 8192), 16, 0, 0); } while (0)
; #define PG8_LDA(dst, b, h) do { _Pragma("unroll") for (int m = 0; m < 4; ++m) _Pragma("unroll") for (int k = 0; k < 2; ++k) dst[m][k] = *(const PG8_LAS bf16x8*)(lds + PG8_SA(b, h) + aoff + m * 2048 + k * 1024); } while (0)
; #define PG8_LDB(dst, b, h) do { _Pragma("unroll") for (int n = 0; n < 2; ++n) _Pragma("unroll") for (int k = 0; k < 2; ++k) dst[n][k] = *(const PG8_LAS bf16x8*)(lds + PG8_SB(b, h) + boff + n * 2048 + k * 1024); } while (0)
; #define PG8_MMA(ai, bj, At, Bt) do { __builtin_amdgcn_s_setprio(1); _Pragma("unroll") for (int m = 0; m < 4; ++m) _Pragma("unroll") for (int n = 0; n < 2; ++n) _Pragma("unroll") for (int k = 0; k < 2; ++k) \
;         acc[ai][bj][m][n] = __builtin_amdgcn_mfma_f32_16x16x32_bf16(Bt[n][k], At[m][k], acc[ai][bj][m][n], 0, 0, 0); __builtin_amdgcn_s_setprio(0); } while (0)
; #define PG8_WAIT_V(n) asm volatile("s_waitcnt vmcnt(" #n ")" ::: "memory")
; #define PG8_WAIT_L(n) asm volatile("s_waitcnt lgkmcnt(" #n ")" ::: "memory")
; #define PG8_BAR __builtin_amdgcn_s_barrier()
; #define PG8_SCHED __builtin_amdgcn_sched_barrier(0)
; template <class Epi, class Sched, bool ALIGN_EPI = false, bool SP2 = false>
; __device__ __forceinline__ void gemm_phase(PG8_LAS unsigned char* lds, const Gemm g, const Sched& S, const Epi& E, const int wave0) {
;     ...
;             PG8_WAIT_V(8); PG8_WAIT_L(0); PG8_BAR; PG8_MMA(1, 0, At, B0); PG8_MMA(1, 1, At, B1); PG8_BAR; PG8_SCHED;
;             PG8_LDB(B0, 1, 0); PG8_LDB(B1, 1, 1); PG8_SCHED; PG8_LDA(At, 1, 0); PG8_STAGE(PG8_SA(0, 1), a2 + hstep, voffA);
;             PG8_WAIT_V(8); PG8_WAIT_L(0); PG8_BAR; PG8_MMA(0, 0, At, B0); PG8_MMA(0, 1, At, B1); PG8_BAR; PG8_SCHED;
	s_setprio 1
	v_mfma_f32_16x16x32_bf16 v[60:63], v[64:67], v[160:163], v[60:63]
	v_mfma_f32_16x16x32_bf16 v[52:55], v[136:139], v[160:163], v[52:55]
	v_mfma_f32_16x16x32_bf16 v[44:47], v[64:67], v[168:171], v[44:47]
	v_mfma_f32_16x16x32_bf16 v[36:39], v[136:139], v[168:171], v[36:39]
	v_mfma_f32_16x16x32_bf16 v[28:31], v[64:67], v[176:179], v[28:31]
	v_mfma_f32_16x16x32_bf16 v[20:23], v[136:139], v[176:179], v[20:23]
	v_mfma_f32_16x16x32_bf16 v[12:15], v[64:67], v[184:187], v[12:15]
	v_mfma_f32_16x16x32_bf16 v[4:7], v[136:139], v[184:187], v[4:7]
	v_mfma_f32_16x16x32_bf16 v[60:63], v[132:135], v[164:167], v[60:63]
	v_mfma_f32_16x16x32_bf16 v[52:55], v[140:143], v[164:167], v[52:55]
	v_mfma_f32_16x16x32_bf16 v[44:47], v[132:135], v[172:175], v[44:47]
	v_mfma_f32_16x16x32_bf16 v[36:39], v[140:143], v[172:175], v[36:39]
	v_mfma_f32_16x16x32_bf16 v[28:31], v[132:135], v[180:183], v[28:31]
	v_mfma_f32_16x16x32_bf16 v[20:23], v[140:143], v[180:183], v[20:23]
	v_mfma_f32_16x16x32_bf16 v[12:15], v[132:135], v[188:191], v[12:15]
	v_mfma_f32_16x16x32_bf16 v[4:7], v[140:143], v[188:191], v[4:7]
	v_mfma_f32_16x16x32_bf16 v[56:59], v[144:147], v[160:163], v[56:59]
	v_mfma_f32_16x16x32_bf16 v[48:51], v[152:155], v[160:163], v[48:51]
	v_mfma_f32_16x16x32_bf16 v[40:43], v[144:147], v[168:171], v[40:43]
	v_mfma_f32_16x16x32_bf16 v[32:35], v[152:155], v[168:171], v[32:35]
	v_mfma_f32_16x16x32_bf16 v[24:27], v[144:147], v[176:179], v[24:27]
	v_mfma_f32_16x16x32_bf16 v[16:19], v[152:155], v[176:179], v[16:19]
	v_mfma_f32_16x16x32_bf16 v[8:11], v[144:147], v[184:187], v[8:11]
	v_mfma_f32_16x16x32_bf16 v[0:3], v[152:155], v[184:187], v[0:3]
	v_mfma_f32_16x16x32_bf16 v[56:59], v[148:151], v[164:167], v[56:59]
	v_mfma_f32_16x16x32_bf16 v[48:51], v[156:159], v[164:167], v[48:51]
	v_mfma_f32_16x16x32_bf16 v[40:43], v[148:151], v[172:175], v[40:43]
	v_mfma_f32_16x16x32_bf16 v[32:35], v[156:159], v[172:175], v[32:35]
	v_mfma_f32_16x16x32_bf16 v[24:27], v[148:151], v[180:183], v[24:27]
	v_mfma_f32_16x16x32_bf16 v[16:19], v[156:159], v[180:183], v[16:19]
	v_mfma_f32_16x16x32_bf16 v[8:11], v[148:151], v[188:191], v[8:11]
	v_mfma_f32_16x16x32_bf16 v[0:3], v[156:159], v[188:191], v[0:3]
	s_setprio 0
	s_barrier
	v_add_u32_e32 v140, s86, v238
	v_add_u32_e32 v156, s80, v238
	ds_read_b128 v[64:67], v140
	ds_read_b128 v[132:135], v140 offset:1024
	ds_read_b128 v[136:139], v140 offset:2048
	ds_read_b128 v[140:143], v140 offset:3072
	ds_read_b128 v[144:147], v156
	ds_read_b128 v[148:151], v156 offset:1024
	ds_read_b128 v[152:155], v156 offset:2048
	ds_read_b128 v[156:159], v156 offset:3072
	s_mov_b32 m0, s23
	ds_read_b128 v[160:163], v239 offset:32768
	ds_read_b128 v[164:167], v239 offset:33792
	ds_read_b128 v[168:171], v239 offset:34816
	ds_read_b128 v[172:175], v239 offset:35840
	ds_read_b128 v[176:179], v239 offset:36864
	ds_read_b128 v[180:183], v239 offset:37888
	ds_read_b128 v[184:187], v239 offset:38912
	ds_read_b128 v[188:191], v239 offset:39936
	global_load_lds_dwordx4 v216, s[58:59]
	s_mov_b32 m0, s83
	s_nop 0
	global_load_lds_dwordx4 v218, s[58:59]
	s_waitcnt vmcnt(8)
	s_waitcnt lgkmcnt(0)
	s_barrier
	s_setprio 1
	v_mfma_f32_16x16x32_bf16 v[128:131], v[64:67], v[160:163], v[128:131]
	v_mfma_f32_16x16x32_bf16 v[124:127], v[136:139], v[160:163], v[124:127]
	v_mfma_f32_16x16x32_bf16 v[112:115], v[64:67], v[168:171], v[112:115]
	v_mfma_f32_16x16x32_bf16 v[104:107], v[136:139], v[168:171], v[104:107]
	v_mfma_f32_16x16x32_bf16 v[96:99], v[64:67], v[176:179], v[96:99]
	v_mfma_f32_16x16x32_bf16 v[88:91], v[136:139], v[176:179], v[88:91]
	v_mfma_f32_16x16x32_bf16 v[80:83], v[64:67], v[184:187], v[80:83]
	v_mfma_f32_16x16x32_bf16 v[72:75], v[136:139], v[184:187], v[72:75]
	v_mfma_f32_16x16x32_bf16 v[128:131], v[132:135], v[164:167], v[128:131]
	v_mfma_f32_16x16x32_bf16 v[124:127], v[140:143], v[164:167], v[124:127]
	v_mfma_f32_16x16x32_bf16 v[112:115], v[132:135], v[172:175], v[112:115]
	v_mfma_f32_16x16x32_bf16 v[104:107], v[140:143], v[172:175], v[104:107]
	v_mfma_f32_16x16x32_bf16 v[96:99], v[132:135], v[180:183], v[96:99]
	v_mfma_f32_16x16x32_bf16 v[88:91], v[140:143], v[180:183], v[88:91]
	v_mfma_f32_16x16x32_bf16 v[80:83], v[132:135], v[188:191], v[80:83]
	v_mfma_f32_16x16x32_bf16 v[72:75], v[140:143], v[188:191], v[72:75]
	v_mfma_f32_16x16x32_bf16 v[120:123], v[144:147], v[160:163], v[120:123]
	v_mfma_f32_16x16x32_bf16 v[116:119], v[152:155], v[160:163], v[116:119]
	v_mfma_f32_16x16x32_bf16 v[108:111], v[144:147], v[168:171], v[108:111]
	v_mfma_f32_16x16x32_bf16 v[100:103], v[152:155], v[168:171], v[100:103]
	v_mfma_f32_16x16x32_bf16 v[92:95], v[144:147], v[176:179], v[92:95]
	v_mfma_f32_16x16x32_bf16 v[84:87], v[152:155], v[176:179], v[84:87]
	v_mfma_f32_16x16x32_bf16 v[76:79], v[144:147], v[184:187], v[76:79]
	v_mfma_f32_16x16x32_bf16 v[68:71], v[152:155], v[184:187], v[68:71]
	v_mfma_f32_16x16x32_bf16 v[120:123], v[148:151], v[164:167], v[120:123]
	v_mfma_f32_16x16x32_bf16 v[116:119], v[156:159], v[164:167], v[116:119]
	v_mfma_f32_16x16x32_bf16 v[108:111], v[148:151], v[172:175], v[108:111]
	v_mfma_f32_16x16x32_bf16 v[100:103], v[156:159], v[172:175], v[100:103]
	v_mfma_f32_16x16x32_bf16 v[92:95], v[148:151], v[180:183], v[92:95]
	v_mfma_f32_16x16x32_bf16 v[84:87], v[156:159], v[180:183], v[84:87]
	v_mfma_f32_16x16x32_bf16 v[76:79], v[148:151], v[188:191], v[76:79]
	v_mfma_f32_16x16x32_bf16 v[68:71], v[156:159], v[188:191], v[68:71]
	s_setprio 0
	s_barrier
; #define PG8_STAGE(bufoff, gbase, voff) do { _Pragma("unroll") for (int _i = 0; _i < 2; ++_i) \
;         __builtin_amdgcn_global_load_lds((const unsigned*)((const char*)(gbase) + (voff)[_i]), (PG8_LAS unsigned*)(lds + (bufoff) + ldsw + _i * 8192), 16, 0, 0); } while (0)
; #define PG8_LDA(dst, b, h) do { _Pragma("unroll") for (int m = 0; m < 4; ++m) _Pragma("unroll") for (int k = 0; k < 2; ++k) dst[m][k] = *(const PG8_LAS bf16x8*)(lds + PG8_SA(b, h) + aoff + m * 2048 + k * 1024); } while (0)
; #define PG8_BAR __builtin_amdgcn_s_barrier()
; template <class Epi, class Sched, bool ALIGN_EPI = false, bool SP2 = false>
; __device__ __forceinline__ void gemm_phase(PG8_LAS unsigned char* lds, const Gemm g, const Sched& S, const Epi& E, const int wave0) {
;     ...
;             PG8_LDA(At, 1, 1); PG8_STAGE(PG8_SB(1, 0), b3, voffB); PG8_STAGE(PG8_SB(1, 1), b3 + hstep, voffB); PG8_STAGE(PG8_SA(1, 0), a3, voffA);
;             PG8_WAIT_V(8); PG8_WAIT_L(0); PG8_BAR; PG8_MMA(1, 0, At, B0); PG8_MMA(1, 1, At, B1); PG8_BAR; PG8_SCHED;
;             } else {
;             PG8_LDB(B0, 0, 0); PG8_SCHED; PG8_LDA(At, 0, 0); PG8_STAGE(PG8_SA(1, 1), a1 + hstep, voffA);
;             PG8_WAIT_L(8); PG8_BAR; PG8_WAIT_L(0); PG8_MMA(0, 0, At, B0); PG8_BAR; PG8_SCHED;
;             PG8_LDB(B1, 0, 1); PG8_STAGE(PG8_SB(0, 0), b2, voffB);
;             PG8_BAR; PG8_WAIT_L(0); PG8_MMA(0, 1, At, B1); PG8_BAR;
;             PG8_LDA(At, 0, 1); PG8_STAGE(PG8_SA(0, 0), a2, voffA);
;             PG8_BAR; PG8_WAIT_L(0); PG8_MMA(1, 0, At, B0); PG8_BAR; PG8_SCHED;
;             PG8_STAGE(PG8_SB(0, 1), b2 + hstep, voffB);
;             PG8_WAIT_V(6); PG8_BAR; PG8_MMA(1, 1, At, B1); PG8_BAR;
;             PG8_LDB(B0, 1, 0); PG8_SCHED; PG8_LDA(At, 1, 0); PG8_STAGE(PG8_SA(0, 1), a2 + hstep, voffA);
;             PG8_WAIT_L(8); PG8_BAR; PG8_WAIT_L(0); PG8_MMA(0, 0, At, B0); PG8_BAR; PG8_SCHED;
;             PG8_LDB(B1, 1, 1); PG8_STAGE(PG8_SB(1, 0), b3, voffB);
;             PG8_BAR; PG8_WAIT_L(0); PG8_MMA(0, 1, At, B1); PG8_BAR;
;             PG8_LDA(At, 1, 1); PG8_STAGE(PG8_SA(1, 0), a3, voffA);
;             PG8_BAR; PG8_WAIT_L(0); PG8_MMA(1, 0, At, B0); PG8_BAR; PG8_SCHED;
;             PG8_STAGE(PG8_SB(1, 1), b3 + hstep, voffB);
;             PG8_WAIT_V(6); PG8_BAR; PG8_MMA(1, 1, At, B1); PG8_BAR;
;             }
;         }
;         if constexpr (ALIGN_EPI) { if (wr == 0) PG8_BAR; }
	s_add_i32 m0, s74, 0xffffff80
	ds_read_b128 v[160:163], v239 offset:49152
	ds_read_b128 v[164:167], v239 offset:50176
	ds_read_b128 v[168:171], v239 offset:51200
	ds_read_b128 v[172:175], v239 offset:52224
	ds_read_b128 v[176:179], v239 offset:53248
	ds_read_b128 v[180:183], v239 offset:54272
	ds_read_b128 v[184:187], v239 offset:55296
	ds_read_b128 v[188:191], v239 offset:56320
	global_load_lds_dwordx4 v216, s[62:63] offset:128
	s_add_i32 m0, s72, 0xffffff80
	s_nop 0
	global_load_lds_dwordx4 v218, s[62:63] offset:128
	s_mov_b32 m0, s19
	s_nop 0
	global_load_lds_dwordx4 v216, s[56:57]
	s_mov_b32 m0, s18
	s_nop 0
	global_load_lds_dwordx4 v218, s[56:57]
	s_add_i32 m0, s53, 0xffffff80
	s_nop 0
	global_load_lds_dwordx4 v216, s[60:61] offset:128
	s_add_i32 m0, s24, 0xffffff80
	s_nop 0
	global_load_lds_dwordx4 v218, s[60:61] offset:128
	s_waitcnt vmcnt(8)
	s_waitcnt lgkmcnt(0)
	s_barrier
	s_setprio 1
	v_mfma_f32_16x16x32_bf16 v[60:63], v[64:67], v[160:163], v[60:63]
	v_mfma_f32_16x16x32_bf16 v[52:55], v[136:139], v[160:163], v[52:55]
	v_mfma_f32_16x16x32_bf16 v[44:47], v[64:67], v[168:171], v[44:47]
	v_mfma_f32_16x16x32_bf16 v[36:39], v[136:139], v[168:171], v[36:39]
	v_mfma_f32_16x16x32_bf16 v[28:31], v[64:67], v[176:179], v[28:31]
	v_mfma_f32_16x16x32_bf16 v[20:23], v[136:139], v[176:179], v[20:23]
	v_mfma_f32_16x16x32_bf16 v[12:15], v[64:67], v[184:187], v[12:15]
	v_mfma_f32_16x16x32_bf16 v[4:7], v[136:139], v[184:187], v[4:7]
	v_mfma_f32_16x16x32_bf16 v[60:63], v[132:135], v[164:167], v[60:63]
	v_mfma_f32_16x16x32_bf16 v[52:55], v[140:143], v[164:167], v[52:55]
	v_mfma_f32_16x16x32_bf16 v[44:47], v[132:135], v[172:175], v[44:47]
	v_mfma_f32_16x16x32_bf16 v[36:39], v[140:143], v[172:175], v[36:39]
	v_mfma_f32_16x16x32_bf16 v[28:31], v[132:135], v[180:183], v[28:31]
	v_mfma_f32_16x16x32_bf16 v[20:23], v[140:143], v[180:183], v[20:23]
	v_mfma_f32_16x16x32_bf16 v[12:15], v[132:135], v[188:191], v[12:15]
	v_mfma_f32_16x16x32_bf16 v[4:7], v[140:143], v[188:191], v[4:7]
	v_mfma_f32_16x16x32_bf16 v[56:59], v[144:147], v[160:163], v[56:59]
	v_mfma_f32_16x16x32_bf16 v[48:51], v[152:155], v[160:163], v[48:51]
	v_mfma_f32_16x16x32_bf16 v[40:43], v[144:147], v[168:171], v[40:43]
	v_mfma_f32_16x16x32_bf16 v[32:35], v[152:155], v[168:171], v[32:35]
	v_mfma_f32_16x16x32_bf16 v[24:27], v[144:147], v[176:179], v[24:27]
	v_mfma_f32_16x16x32_bf16 v[16:19], v[152:155], v[176:179], v[16:19]
	v_mfma_f32_16x16x32_bf16 v[8:11], v[144:147], v[184:187], v[8:11]
	v_mfma_f32_16x16x32_bf16 v[0:3], v[152:155], v[184:187], v[0:3]
	v_mfma_f32_16x16x32_bf16 v[56:59], v[148:151], v[164:167], v[56:59]
	v_mfma_f32_16x16x32_bf16 v[48:51], v[156:159], v[164:167], v[48:51]
	v_mfma_f32_16x16x32_bf16 v[40:43], v[148:151], v[172:175], v[40:43]
	v_mfma_f32_16x16x32_bf16 v[32:35], v[156:159], v[172:175], v[32:35]
	v_mfma_f32_16x16x32_bf16 v[24:27], v[148:151], v[180:183], v[24:27]
	v_mfma_f32_16x16x32_bf16 v[16:19], v[156:159], v[180:183], v[16:19]
	v_mfma_f32_16x16x32_bf16 v[8:11], v[148:151], v[188:191], v[8:11]
	v_mfma_f32_16x16x32_bf16 v[0:3], v[156:159], v[188:191], v[0:3]
	s_setprio 0
	s_barrier
	s_movk_i32 s58, 0x100
	s_andn2_b64 vcc, exec, s[54:55]
	s_mov_b64 s[56:57], -1
	s_mov_b64 s[54:55], 0
	s_cbranch_vccz .LBB0_1258
	v_readlane_b32 s66, v254, 34
	v_readlane_b32 s67, v254, 35
	s_and_b64 vcc, exec, s[66:67]
	s_cbranch_vccz .LBB0_1261
	s_barrier

; #define PG8_STAGE(bufoff, gbase, voff) do { _Pragma("unroll") for (int _i = 0; _i < 2; ++_i) \
;         __builtin_amdgcn_global_load_lds((const unsigned*)((const char*)(gbase) + (voff)[_i]), (PG8_LAS unsigned*)(lds + (bufoff) + ldsw + _i * 8192), 16, 0, 0); } while (0)
; #define PG8_LDA(dst, b, h) do { _Pragma("unroll") for (int m = 0; m < 4; ++m) _Pragma("unroll") for (int k = 0; k < 2; ++k) dst[m][k] = *(const PG8_LAS bf16x8*)(lds + PG8_SA(b, h) + aoff + m * 2048 + k * 1024); } while (0)
; #define PG8_LDB(dst, b, h) do { _Pragma("unroll") for (int n = 0; n < 2; ++n) _Pragma("unroll") for (int k = 0; k < 2; ++k) dst[n][k] = *(const PG8_LAS bf16x8*)(lds + PG8_SB(b, h) + boff + n * 2048 + k * 1024); } while (0)
; #define PG8_WAIT_V(n) asm volatile("s_waitcnt vmcnt(" #n ")" ::: "memory")
; #define PG8_WAIT_L(n) asm volatile("s_waitcnt lgkmcnt(" #n ")" ::: "memory")
; #define PG8_BAR __builtin_amdgcn_s_barrier()
; #define PG8_SCHED __builtin_amdgcn_sched_barrier(0)
; template <class Epi, class Sched, bool ALIGN_EPI = false, bool SP2 = false>
; __device__ __forceinline__ void gemm_phase(PG8_LAS unsigned char* lds, const Gemm g, const Sched& S, const Epi& E, const int wave0) {
;     ...
;         const char* nA = has_next ? (const char*)g.A + (size_t)nxt.pm * tstep : cA; const char* nB = has_next ? (const char*)g.Bt + (size_t)nxt.pn * tstep : cB;
;         for (int t = 0; t < nt; t += 2) {
;             const bool last = (t == nt - 2);
;             const char* a1 = cA + (size_t)(t + 1) * kstep;
;             const char* a2 = last ? nA : cA + (size_t)(t + 2) * kstep; const char* b2 = last ? nB : cB + (size_t)(t + 2) * kstep;
;             const char* a3 = a2 + kstep; const char* b3 = b2 + kstep;
;             if (last && has_next) S.a_ready(nxt);
;             if constexpr (SP2) {
;             PG8_LDB(B0, 0, 0); PG8_LDB(B1, 0, 1); PG8_SCHED; PG8_LDA(At, 0, 0); PG8_STAGE(PG8_SA(1, 1), a1 + hstep, voffA);
;             PG8_WAIT_V(8); PG8_WAIT_L(0); PG8_BAR; PG8_MMA(0, 0, At, B0); PG8_MMA(0, 1, At, B1); PG8_BAR; PG8_SCHED;
;             PG8_LDA(At, 0, 1); PG8_STAGE(PG8_SB(0, 0), b2, voffB); PG8_STAGE(PG8_SB(0, 1), b2 + hstep, voffB); PG8_STAGE(PG8_SA(0, 0), a2, voffA);
;             PG8_WAIT_V(8); PG8_WAIT_L(0); PG8_BAR; PG8_MMA(1, 0, At, B0); PG8_MMA(1, 1, At, B1); PG8_BAR; PG8_SCHED;
.LBB0_1659:
	s_add_u32 s12, s10, 0x100
	s_addc_u32 s13, s11, 0
	s_add_i32 s18, 0, 0x10000
	s_cmp_eq_u32 s59, 28
	s_cselect_b32 s57, s9, s13
	s_cselect_b32 s56, s16, s12
	s_cselect_b32 s55, s17, s58
	s_cselect_b32 s54, s45, s47
	s_add_i32 s19, 0, 0x14000
	v_add_u32_e32 v140, s18, v242
	v_add_u32_e32 v156, s19, v242
	ds_read_b128 v[64:67], v140
	ds_read_b128 v[132:135], v140 offset:1024
	ds_read_b128 v[136:139], v140 offset:2048
	ds_read_b128 v[140:143], v140 offset:3072
	ds_read_b128 v[144:147], v156
	ds_read_b128 v[148:151], v156 offset:1024
	ds_read_b128 v[152:155], v156 offset:2048
	ds_read_b128 v[156:159], v156 offset:3072
	s_add_i32 m0, s33, 0xc000
	ds_read_b128 v[160:163], v243
	ds_read_b128 v[164:167], v243 offset:1024
	ds_read_b128 v[168:171], v243 offset:2048
	ds_read_b128 v[172:175], v243 offset:3072
	ds_read_b128 v[176:179], v243 offset:4096
	ds_read_b128 v[180:183], v243 offset:5120
	ds_read_b128 v[184:187], v243 offset:6144
	ds_read_b128 v[188:191], v243 offset:7168
	global_load_lds_dwordx4 v222, s[10:11]
	s_add_i32 m0, s33, 0xe000
	s_nop 0
	global_load_lds_dwordx4 v224, s[10:11]
	s_waitcnt vmcnt(8)
	s_waitcnt lgkmcnt(0)
	s_barrier
	s_setprio 1
	v_mfma_f32_16x16x32_bf16 v[128:131], v[64:67], v[160:163], v[128:131]
	v_mfma_f32_16x16x32_bf16 v[124:127], v[136:139], v[160:163], v[124:127]
	v_mfma_f32_16x16x32_bf16 v[112:115], v[64:67], v[168:171], v[112:115]
	v_mfma_f32_16x16x32_bf16 v[104:107], v[136:139], v[168:171], v[104:107]
	v_mfma_f32_16x16x32_bf16 v[96:99], v[64:67], v[176:179], v[96:99]
	v_mfma_f32_16x16x32_bf16 v[88:91], v[136:139], v[176:179], v[88:91]
	v_mfma_f32_16x16x32_bf16 v[80:83], v[64:67], v[184:187], v[80:83]
	v_mfma_f32_16x16x32_bf16 v[72:75], v[136:139], v[184:187], v[72:75]
	v_mfma_f32_16x16x32_bf16 v[128:131], v[132:135], v[164:167], v[128:131]
	v_mfma_f32_16x16x32_bf16 v[124:127], v[140:143], v[164:167], v[124:127]
	v_mfma_f32_16x16x32_bf16 v[112:115], v[132:135], v[172:175], v[112:115]
	v_mfma_f32_16x16x32_bf16 v[104:107], v[140:143], v[172:175], v[104:107]
	v_mfma_f32_16x16x32_bf16 v[96:99], v[132:135], v[180:183], v[96:99]
	v_mfma_f32_16x16x32_bf16 v[88:91], v[140:143], v[180:183], v[88:91]
	v_mfma_f32_16x16x32_bf16 v[80:83], v[132:135], v[188:191], v[80:83]
	v_mfma_f32_16x16x32_bf16 v[72:75], v[140:143], v[188:191], v[72:75]
	v_mfma_f32_16x16x32_bf16 v[120:123], v[144:147], v[160:163], v[120:123]
	v_mfma_f32_16x16x32_bf16 v[116:119], v[152:155], v[160:163], v[116:119]
	v_mfma_f32_16x16x32_bf16 v[108:111], v[144:147], v[168:171], v[108:111]
	v_mfma_f32_16x16x32_bf16 v[100:103], v[152:155], v[168:171], v[100:103]
	v_mfma_f32_16x16x32_bf16 v[92:95], v[144:147], v[176:179], v[92:95]
	v_mfma_f32_16x16x32_bf16 v[84:87], v[152:155], v[176:179], v[84:87]
	v_mfma_f32_16x16x32_bf16 v[76:79], v[144:147], v[184:187], v[76:79]
	v_mfma_f32_16x16x32_bf16 v[68:71], v[152:155], v[184:187], v[68:71]
	v_mfma_f32_16x16x32_bf16 v[120:123], v[148:151], v[164:167], v[120:123]
	v_mfma_f32_16x16x32_bf16 v[116:119], v[156:159], v[164:167], v[116:119]
	v_mfma_f32_16x16x32_bf16 v[108:111], v[148:151], v[172:175], v[108:111]
	v_mfma_f32_16x16x32_bf16 v[100:103], v[156:159], v[172:175], v[100:103]
	v_mfma_f32_16x16x32_bf16 v[92:95], v[148:151], v[180:183], v[92:95]
	v_mfma_f32_16x16x32_bf16 v[84:87], v[156:159], v[180:183], v[84:87]
	v_mfma_f32_16x16x32_bf16 v[76:79], v[148:151], v[188:191], v[76:79]
	v_mfma_f32_16x16x32_bf16 v[68:71], v[156:159], v[188:191], v[68:71]
	s_setprio 0
	s_barrier
	s_add_i32 s10, s18, s95
	s_mov_b32 m0, s10
	ds_read_b128 v[160:163], v243 offset:16384
	ds_read_b128 v[164:167], v243 offset:17408
	ds_read_b128 v[168:171], v243 offset:18432
	ds_read_b128 v[172:175], v243 offset:19456
	ds_read_b128 v[176:179], v243 offset:20480
	ds_read_b128 v[180:183], v243 offset:21504
	ds_read_b128 v[184:187], v243 offset:22528
	ds_read_b128 v[188:191], v243 offset:23552
	global_load_lds_dwordx4 v216, s[54:55]
	s_add_i32 m0, s10, 0x2000
	s_add_u32 s10, s54, 0x80000
	s_addc_u32 s11, s55, 0
	s_add_i32 s18, s19, s95
	global_load_lds_dwordx4 v218, s[54:55]
	s_mov_b32 m0, s18
	s_nop 0
	global_load_lds_dwordx4 v216, s[10:11]
	s_add_i32 m0, s18, 0x2000
	s_nop 0
	global_load_lds_dwordx4 v218, s[10:11]
	s_mov_b32 m0, s33
	s_nop 0
	global_load_lds_dwordx4 v216, s[56:57]
	s_mov_b32 m0, s82
	s_nop 0
	global_load_lds_dwordx4 v218, s[56:57]
	s_waitcnt vmcnt(8)
	s_waitcnt lgkmcnt(0)
	s_barrier
	s_setprio 1
	v_mfma_f32_16x16x32_bf16 v[60:63], v[64:67], v[160:163], v[60:63]
	v_mfma_f32_16x16x32_bf16 v[52:55], v[136:139], v[160:163], v[52:55]
	v_mfma_f32_16x16x32_bf16 v[44:47], v[64:67], v[168:171], v[44:47]
	v_mfma_f32_16x16x32_bf16 v[36:39], v[136:139], v[168:171], v[36:39]
	v_mfma_f32_16x16x32_bf16 v[28:31], v[64:67], v[176:179], v[28:31]
	v_mfma_f32_16x16x32_bf16 v[20:23], v[136:139], v[176:179], v[20:23]
	v_mfma_f32_16x16x32_bf16 v[12:15], v[64:67], v[184:187], v[12:15]
	v_mfma_f32_16x16x32_bf16 v[4:7], v[136:139], v[184:187], v[4:7]
	v_mfma_f32_16x16x32_bf16 v[60:63], v[132:135], v[164:167], v[60:63]
	v_mfma_f32_16x16x32_bf16 v[52:55], v[140:143], v[164:167], v[52:55]
	v_mfma_f32_16x16x32_bf16 v[44:47], v[132:135], v[172:175], v[44:47]
	v_mfma_f32_16x16x32_bf16 v[36:39], v[140:143], v[172:175], v[36:39]
	v_mfma_f32_16x16x32_bf16 v[28:31], v[132:135], v[180:183], v[28:31]
	v_mfma_f32_16x16x32_bf16 v[20:23], v[140:143], v[180:183], v[20:23]
	v_mfma_f32_16x16x32_bf16 v[12:15], v[132:135], v[188:191], v[12:15]
	v_mfma_f32_16x16x32_bf16 v[4:7], v[140:143], v[188:191], v[4:7]
	v_mfma_f32_16x16x32_bf16 v[56:59], v[144:147], v[160:163], v[56:59]
	v_mfma_f32_16x16x32_bf16 v[48:51], v[152:155], v[160:163], v[48:51]
	v_mfma_f32_16x16x32_bf16 v[40:43], v[144:147], v[168:171], v[40:43]
	v_mfma_f32_16x16x32_bf16 v[32:35], v[152:155], v[168:171], v[32:35]
	v_mfma_f32_16x16x32_bf16 v[24:27], v[144:147], v[176:179], v[24:27]
	v_mfma_f32_16x16x32_bf16 v[16:19], v[152:155], v[176:179], v[16:19]
	v_mfma_f32_16x16x32_bf16 v[8:11], v[144:147], v[184:187], v[8:11]
	v_mfma_f32_16x16x32_bf16 v[0:3], v[152:155], v[184:187], v[0:3]
	v_mfma_f32_16x16x32_bf16 v[56:59], v[148:151], v[164:167], v[56:59]
	v_mfma_f32_16x16x32_bf16 v[48:51], v[156:159], v[164:167], v[48:51]
	v_mfma_f32_16x16x32_bf16 v[40:43], v[148:151], v[172:175], v[40:43]
	v_mfma_f32_16x16x32_bf16 v[32:35], v[156:159], v[172:175], v[32:35]
	v_mfma_f32_16x16x32_bf16 v[24:27], v[148:151], v[180:183], v[24:27]
	v_mfma_f32_16x16x32_bf16 v[16:19], v[156:159], v[180:183], v[16:19]
	v_mfma_f32_16x16x32_bf16 v[8:11], v[148:151], v[188:191], v[8:11]
	v_mfma_f32_16x16x32_bf16 v[0:3], v[156:159], v[188:191], v[0:3]
	s_setprio 0
	s_barrier
; #define PG8_STAGE(bufoff, gbase, voff) do { _Pragma("unroll") for (int _i = 0; _i < 2; ++_i) \
;         __builtin_amdgcn_global_load_lds((const unsigned*)((const char*)(gbase) + (voff)[_i]), (PG8_LAS unsigned*)(lds + (bufoff) + ldsw + _i * 8192), 16, 0, 0); } while (0)
; #define PG8_BAR __builtin_amdgcn_s_barrier()
; template <class Epi, class Sched, bool ALIGN_EPI = false, bool SP2 = false>
; __device__ __forceinline__ void gemm_phase(PG8_LAS unsigned char* lds, const Gemm g, const Sched& S, const Epi& E, const int wave0) {
;     ...
;             PG8_LDB(B0, 1, 0); PG8_LDB(B1, 1, 1); PG8_SCHED; PG8_LDA(At, 1, 0); PG8_STAGE(PG8_SA(0, 1), a2 + hstep, voffA);
;             PG8_WAIT_V(8); PG8_WAIT_L(0); PG8_BAR; PG8_MMA(0, 0, At, B0); PG8_MMA(0, 1, At, B1); PG8_BAR; PG8_SCHED;
;             PG8_LDA(At, 1, 1); PG8_STAGE(PG8_SB(1, 0), b3, voffB); PG8_STAGE(PG8_SB(1, 1), b3 + hstep, voffB); PG8_STAGE(PG8_SA(1, 0), a3, voffA);
;             PG8_WAIT_V(8); PG8_WAIT_L(0); PG8_BAR; PG8_MMA(1, 0, At, B0); PG8_MMA(1, 1, At, B1); PG8_BAR; PG8_SCHED;
;             } else {
;             PG8_LDB(B0, 0, 0); PG8_SCHED; PG8_LDA(At, 0, 0); PG8_STAGE(PG8_SA(1, 1), a1 + hstep, voffA);
;             PG8_WAIT_L(8); PG8_BAR; PG8_WAIT_L(0); PG8_MMA(0, 0, At, B0); PG8_BAR; PG8_SCHED;
;             PG8_LDB(B1, 0, 1); PG8_STAGE(PG8_SB(0, 0), b2, voffB);
;             PG8_BAR; PG8_WAIT_L(0); PG8_MMA(0, 1, At, B1); PG8_BAR;
;             PG8_LDA(At, 0, 1); PG8_STAGE(PG8_SA(0, 0), a2, voffA);
;             PG8_BAR; PG8_WAIT_L(0); PG8_MMA(1, 0, At, B0); PG8_BAR; PG8_SCHED;
;             PG8_STAGE(PG8_SB(0, 1), b2 + hstep, voffB);
;             PG8_WAIT_V(6); PG8_BAR; PG8_MMA(1, 1, At, B1); PG8_BAR;
;             PG8_LDB(B0, 1, 0); PG8_SCHED; PG8_LDA(At, 1, 0); PG8_STAGE(PG8_SA(0, 1), a2 + hstep, voffA);
;             PG8_WAIT_L(8); PG8_BAR; PG8_WAIT_L(0); PG8_MMA(0, 0, At, B0); PG8_BAR; PG8_SCHED;
;             PG8_LDB(B1, 1, 1); PG8_STAGE(PG8_SB(1, 0), b3, voffB);
;             PG8_BAR; PG8_WAIT_L(0); PG8_MMA(0, 1, At, B1); PG8_BAR;
;             PG8_LDA(At, 1, 1); PG8_STAGE(PG8_SA(1, 0), a3, voffA);
;             PG8_BAR; PG8_WAIT_L(0); PG8_MMA(1, 0, At, B0); PG8_BAR; PG8_SCHED;
;             PG8_STAGE(PG8_SB(1, 1), b3 + hstep, voffB);
;             PG8_WAIT_V(6); PG8_BAR; PG8_MMA(1, 1, At, B1); PG8_BAR;
;             }
;         }
;         if constexpr (ALIGN_EPI) { if (wr == 0) PG8_BAR; }
	s_add_i32 s18, 0, 0x18000
	s_add_i32 s19, 0, 0x1c000
	v_add_u32_e32 v140, s18, v242
	v_add_u32_e32 v156, s19, v242
	ds_read_b128 v[64:67], v140
	ds_read_b128 v[132:135], v140 offset:1024
	ds_read_b128 v[136:139], v140 offset:2048
	ds_read_b128 v[140:143], v140 offset:3072
	ds_read_b128 v[144:147], v156
	ds_read_b128 v[148:151], v156 offset:1024
	ds_read_b128 v[152:155], v156 offset:2048
	ds_read_b128 v[156:159], v156 offset:3072
	s_add_u32 s10, s56, 0x80000
	s_addc_u32 s11, s57, 0
	s_mov_b32 m0, s22
	ds_read_b128 v[160:163], v243 offset:32768
	ds_read_b128 v[164:167], v243 offset:33792
	ds_read_b128 v[168:171], v243 offset:34816
	ds_read_b128 v[172:175], v243 offset:35840
	ds_read_b128 v[176:179], v243 offset:36864
	ds_read_b128 v[180:183], v243 offset:37888
	ds_read_b128 v[184:187], v243 offset:38912
	ds_read_b128 v[188:191], v243 offset:39936
	global_load_lds_dwordx4 v216, s[10:11]
	s_mov_b32 m0, s83
	s_nop 0
	global_load_lds_dwordx4 v218, s[10:11]
	s_waitcnt vmcnt(8)
	s_waitcnt lgkmcnt(0)
	s_barrier
	s_setprio 1
	v_mfma_f32_16x16x32_bf16 v[128:131], v[64:67], v[160:163], v[128:131]
	v_mfma_f32_16x16x32_bf16 v[124:127], v[136:139], v[160:163], v[124:127]
	v_mfma_f32_16x16x32_bf16 v[112:115], v[64:67], v[168:171], v[112:115]
	v_mfma_f32_16x16x32_bf16 v[104:107], v[136:139], v[168:171], v[104:107]
	v_mfma_f32_16x16x32_bf16 v[96:99], v[64:67], v[176:179], v[96:99]
	v_mfma_f32_16x16x32_bf16 v[88:91], v[136:139], v[176:179], v[88:91]
	v_mfma_f32_16x16x32_bf16 v[80:83], v[64:67], v[184:187], v[80:83]
	v_mfma_f32_16x16x32_bf16 v[72:75], v[136:139], v[184:187], v[72:75]
	v_mfma_f32_16x16x32_bf16 v[128:131], v[132:135], v[164:167], v[128:131]
	v_mfma_f32_16x16x32_bf16 v[124:127], v[140:143], v[164:167], v[124:127]
	v_mfma_f32_16x16x32_bf16 v[112:115], v[132:135], v[172:175], v[112:115]
	v_mfma_f32_16x16x32_bf16 v[104:107], v[140:143], v[172:175], v[104:107]
	v_mfma_f32_16x16x32_bf16 v[96:99], v[132:135], v[180:183], v[96:99]
	v_mfma_f32_16x16x32_bf16 v[88:91], v[140:143], v[180:183], v[88:91]
	v_mfma_f32_16x16x32_bf16 v[80:83], v[132:135], v[188:191], v[80:83]
	v_mfma_f32_16x16x32_bf16 v[72:75], v[140:143], v[188:191], v[72:75]
	v_mfma_f32_16x16x32_bf16 v[120:123], v[144:147], v[160:163], v[120:123]
	v_mfma_f32_16x16x32_bf16 v[116:119], v[152:155], v[160:163], v[116:119]
	v_mfma_f32_16x16x32_bf16 v[108:111], v[144:147], v[168:171], v[108:111]
	v_mfma_f32_16x16x32_bf16 v[100:103], v[152:155], v[168:171], v[100:103]
	v_mfma_f32_16x16x32_bf16 v[92:95], v[144:147], v[176:179], v[92:95]
	v_mfma_f32_16x16x32_bf16 v[84:87], v[152:155], v[176:179], v[84:87]
	v_mfma_f32_16x16x32_bf16 v[76:79], v[144:147], v[184:187], v[76:79]
	v_mfma_f32_16x16x32_bf16 v[68:71], v[152:155], v[184:187], v[68:71]
	v_mfma_f32_16x16x32_bf16 v[120:123], v[148:151], v[164:167], v[120:123]
	v_mfma_f32_16x16x32_bf16 v[116:119], v[156:159], v[164:167], v[116:119]
	v_mfma_f32_16x16x32_bf16 v[108:111], v[148:151], v[172:175], v[108:111]
	v_mfma_f32_16x16x32_bf16 v[100:103], v[156:159], v[172:175], v[100:103]
	v_mfma_f32_16x16x32_bf16 v[92:95], v[148:151], v[180:183], v[92:95]
	v_mfma_f32_16x16x32_bf16 v[84:87], v[156:159], v[180:183], v[84:87]
	v_mfma_f32_16x16x32_bf16 v[76:79], v[148:151], v[188:191], v[76:79]
	v_mfma_f32_16x16x32_bf16 v[68:71], v[156:159], v[188:191], v[68:71]
	s_setprio 0
	s_barrier
	s_add_i32 s10, s18, s95
	s_add_i32 m0, s10, 0xffffff80
	ds_read_b128 v[160:163], v243 offset:49152
	ds_read_b128 v[164:167], v243 offset:50176
	ds_read_b128 v[168:171], v243 offset:51200
	ds_read_b128 v[172:175], v243 offset:52224
	ds_read_b128 v[176:179], v243 offset:53248
	ds_read_b128 v[180:183], v243 offset:54272
	ds_read_b128 v[184:187], v243 offset:55296
	ds_read_b128 v[188:191], v243 offset:56320
	global_load_lds_dwordx4 v216, s[54:55] offset:128
	s_add_i32 m0, s10, 0x1f80
	s_add_u32 s10, s54, 0x80080
	s_addc_u32 s11, s55, 0
	s_add_i32 s18, s19, s95
	global_load_lds_dwordx4 v218, s[54:55] offset:128
	s_mov_b32 m0, s18
	s_nop 0
	global_load_lds_dwordx4 v216, s[10:11]
	s_add_i32 m0, s18, 0x2000
	s_nop 0
	global_load_lds_dwordx4 v218, s[10:11]
	s_add_i32 m0, s23, 0xffffff80
	s_nop 0
	global_load_lds_dwordx4 v216, s[56:57] offset:128
	s_add_i32 m0, s24, 0xffffff80
	s_nop 0
	global_load_lds_dwordx4 v218, s[56:57] offset:128
	s_waitcnt vmcnt(8)
	s_waitcnt lgkmcnt(0)
	s_barrier
	s_setprio 1
	v_mfma_f32_16x16x32_bf16 v[60:63], v[64:67], v[160:163], v[60:63]
	v_mfma_f32_16x16x32_bf16 v[52:55], v[136:139], v[160:163], v[52:55]
	v_mfma_f32_16x16x32_bf16 v[44:47], v[64:67], v[168:171], v[44:47]
	v_mfma_f32_16x16x32_bf16 v[36:39], v[136:139], v[168:171], v[36:39]
	v_mfma_f32_16x16x32_bf16 v[28:31], v[64:67], v[176:179], v[28:31]
	v_mfma_f32_16x16x32_bf16 v[20:23], v[136:139], v[176:179], v[20:23]
	v_mfma_f32_16x16x32_bf16 v[12:15], v[64:67], v[184:187], v[12:15]
	v_mfma_f32_16x16x32_bf16 v[4:7], v[136:139], v[184:187], v[4:7]
	v_mfma_f32_16x16x32_bf16 v[60:63], v[132:135], v[164:167], v[60:63]
	v_mfma_f32_16x16x32_bf16 v[52:55], v[140:143], v[164:167], v[52:55]
	v_mfma_f32_16x16x32_bf16 v[44:47], v[132:135], v[172:175], v[44:47]
	v_mfma_f32_16x16x32_bf16 v[36:39], v[140:143], v[172:175], v[36:39]
	v_mfma_f32_16x16x32_bf16 v[28:31], v[132:135], v[180:183], v[28:31]
	v_mfma_f32_16x16x32_bf16 v[20:23], v[140:143], v[180:183], v[20:23]
	v_mfma_f32_16x16x32_bf16 v[12:15], v[132:135], v[188:191], v[12:15]
	v_mfma_f32_16x16x32_bf16 v[4:7], v[140:143], v[188:191], v[4:7]
	v_mfma_f32_16x16x32_bf16 v[56:59], v[144:147], v[160:163], v[56:59]
	v_mfma_f32_16x16x32_bf16 v[48:51], v[152:155], v[160:163], v[48:51]
	v_mfma_f32_16x16x32_bf16 v[40:43], v[144:147], v[168:171], v[40:43]
	v_mfma_f32_16x16x32_bf16 v[32:35], v[152:155], v[168:171], v[32:35]
	v_mfma_f32_16x16x32_bf16 v[24:27], v[144:147], v[176:179], v[24:27]
	v_mfma_f32_16x16x32_bf16 v[16:19], v[152:155], v[176:179], v[16:19]
	v_mfma_f32_16x16x32_bf16 v[8:11], v[144:147], v[184:187], v[8:11]
	v_mfma_f32_16x16x32_bf16 v[0:3], v[152:155], v[184:187], v[0:3]
	v_mfma_f32_16x16x32_bf16 v[56:59], v[148:151], v[164:167], v[56:59]
	v_mfma_f32_16x16x32_bf16 v[48:51], v[156:159], v[164:167], v[48:51]
	v_mfma_f32_16x16x32_bf16 v[40:43], v[148:151], v[172:175], v[40:43]
	v_mfma_f32_16x16x32_bf16 v[32:35], v[156:159], v[172:175], v[32:35]
	v_mfma_f32_16x16x32_bf16 v[24:27], v[148:151], v[180:183], v[24:27]
	v_mfma_f32_16x16x32_bf16 v[16:19], v[156:159], v[180:183], v[16:19]
	v_mfma_f32_16x16x32_bf16 v[8:11], v[148:151], v[188:191], v[8:11]
	v_mfma_f32_16x16x32_bf16 v[0:3], v[156:159], v[188:191], v[0:3]
	s_setprio 0
	s_barrier
	s_add_i32 s59, s59, 2
	s_add_u32 s47, s47, 0x100
	s_addc_u32 s58, s58, 0
	s_cmp_gt_u32 s59, 29
	s_mov_b64 s[10:11], s[12:13]
	s_cbranch_scc0 .LBB0_1659
	s_and_b64 vcc, exec, s[66:67]
	s_cbranch_vccz .LBB0_1662
	s_barrier
